# RWKV prep: decay GEMM + exp(-0.6065*sigmoid) + Wd stores hoisted out of the row-block loop (eight w2t fragments loaded once per tile)
# speedup vs baseline: 1.0163x; 1.0012x over previous
; #define LAS __attribute__((address_space(3)))
; __device__ __forceinline__ float sigmoidf_(float x) { return __builtin_amdgcn_rcpf(1.0f + __expf(-x)); }
; __device__ __forceinline__ f32x4 mfma16(bf16x8 a, bf16x8 b, f32x4 c) { return __builtin_amdgcn_mfma_f32_16x16x32_bf16(a, b, c, 0, 0, 0); }
; template <int K>
; __device__ __forceinline__ void row_gemm(f32x4 (&acc)[4], LAS const unsigned char* Arow, const bf16_t* Bt, int fr, int fq) {
;     bf16x8 bw[K / 32][4];
; #pragma unroll
;     for (int ks = 0; ks < K / 32; ++ks)
; #pragma unroll
;         for (int n = 0; n < 4; ++n) bw[ks][n] = *(const bf16x8*)(Bt + (size_t)(16 * n + fr) * K + ks * 32 + fq * 8);
; #pragma unroll
;     for (int n = 0; n < 4; ++n) acc[n] = (f32x4){0.f, 0.f, 0.f, 0.f};
; #pragma unroll
;     for (int ks = 0; ks < K / 32; ++ks) { const bf16x8 a = *(LAS const bf16x8*)(Arow + (ks * 32 + fq * 8) * 2);
; #pragma unroll
;         for (int n = 0; n < 4; ++n) acc[n] = mfma16(bw[ks][n], a, acc[n]); }
; }
; __device__ __forceinline__ void rwkv_prep_tile(LAS unsigned char* lds, const PrepArgs& P, int tt, int tid) {
;     ...
;         row_gemm<64>(acc, LAw + i * SW, P.w2t + (size_t)cb * 64, fr, fq);
; #pragma unroll
;         for (int n = 0; n < 4; ++n) { const f32x4 a0v = *(LAS const f32x4*)(PRM + 1536 + cb + 16 * n + fq4), w0v = *(LAS const f32x4*)(PRM + 2048 + cb + 16 * n + fq4); f32x4 d;
; #pragma unroll
;             for (int j = 0; j < 4; ++j) { aa[n][j] = sigmoidf_(aa[n][j] + a0v[j]); d[j] = __expf(-0.6065306597f * sigmoidf_(acc[n][j] + w0v[j])); }
;             *(f32x4*)(P.Wd + ((size_t)p * SEQ + s0 + i) * 64 + 4 * fq4 + 4 * n) = d; }
.Lp4g_loop:
	v_add_u32_e32 v177, v176, v208
	ds_read_b128 v[82:85], v177
	ds_read_b128 v[86:89], v177 offset:64
	ds_read_b128 v[90:93], v177 offset:128
	ds_read_b128 v[94:97], v177 offset:192
	v_add_u32_e32 v178, s46, v211
	v_lshlrev_b32_e32 v178, 10, v178
	v_lshl_add_u32 v179, v209, 1, v178
	s_waitcnt lgkmcnt(0)
	v_mfma_f32_16x16x32_bf16 v[160:163], v[18:21], v[82:85], 0
	v_mfma_f32_16x16x32_bf16 v[164:167], v[34:37], v[82:85], 0
	v_mfma_f32_16x16x32_bf16 v[168:171], v[50:53], v[82:85], 0
	v_mfma_f32_16x16x32_bf16 v[172:175], v[66:69], v[82:85], 0
	v_mfma_f32_16x16x32_bf16 v[160:163], v[22:25], v[86:89], v[160:163]
	v_mfma_f32_16x16x32_bf16 v[164:167], v[38:41], v[86:89], v[164:167]
	v_mfma_f32_16x16x32_bf16 v[168:171], v[54:57], v[86:89], v[168:171]
	v_mfma_f32_16x16x32_bf16 v[172:175], v[70:73], v[86:89], v[172:175]
	v_mfma_f32_16x16x32_bf16 v[160:163], v[26:29], v[90:93], v[160:163]
	v_mfma_f32_16x16x32_bf16 v[164:167], v[42:45], v[90:93], v[164:167]
	v_mfma_f32_16x16x32_bf16 v[168:171], v[58:61], v[90:93], v[168:171]
	v_mfma_f32_16x16x32_bf16 v[172:175], v[74:77], v[90:93], v[172:175]
	v_mfma_f32_16x16x32_bf16 v[160:163], v[30:33], v[94:97], v[160:163]
	v_mfma_f32_16x16x32_bf16 v[164:167], v[46:49], v[94:97], v[164:167]
	v_mfma_f32_16x16x32_bf16 v[168:171], v[62:65], v[94:97], v[168:171]
	v_mfma_f32_16x16x32_bf16 v[172:175], v[78:81], v[94:97], v[172:175]
	s_nop 7
	s_nop 7
	v_cvt_pk_bf16_f32 v180, v160, v161
	v_cvt_pk_bf16_f32 v181, v162, v163
	global_store_dwordx2 v179, v[180:181], s[20:21]
	v_cvt_pk_bf16_f32 v182, v164, v165
	v_cvt_pk_bf16_f32 v183, v166, v167
	global_store_dwordx2 v179, v[182:183], s[20:21] offset:32
	v_cvt_pk_bf16_f32 v184, v168, v169
	v_cvt_pk_bf16_f32 v185, v170, v171
	global_store_dwordx2 v179, v[184:185], s[20:21] offset:64
	v_cvt_pk_bf16_f32 v186, v172, v173
	v_cvt_pk_bf16_f32 v187, v174, v175
	global_store_dwordx2 v179, v[186:187], s[20:21] offset:96
	v_add_u32_e32 v176, 0x1100, v176
	s_add_i32 s46, s46, 16
	s_cmp_lg_u32 s46, 64
	s_cbranch_scc1 .Lp4g_loop
	global_load_dwordx4 v[18:21], v[118:119], off
	global_load_dwordx4 v[22:25], v[118:119], off offset:64
	global_load_dwordx4 v[26:29], v[118:119], off offset:2048
	global_load_dwordx4 v[30:33], v[118:119], off offset:2112
	global_load_dwordx4 v[34:37], v[120:121], off
	global_load_dwordx4 v[38:41], v[124:125], off
	global_load_dwordx4 v[42:45], v[122:123], off
	global_load_dwordx4 v[46:49], v[126:127], off
	v_lshlrev_b32_e32 v92, 2, v209
	v_add_u32_e32 v93, s34, v92
	ds_read_b128 v[58:61], v93
	ds_read_b128 v[62:65], v93 offset:64
	ds_read_b128 v[66:69], v93 offset:128
	ds_read_b128 v[70:73], v93 offset:192
	v_lshl_add_u64 v[90:91], v[156:157], 0, s[10:11]
	v_lshlrev_b32_e32 v92, 4, v209
	v_mov_b32_e32 v93, v1
	s_nop 0
	v_lshl_add_u64 v[90:91], v[90:91], 0, v[92:93]
	s_mov_b64 s[48:49], 0xe100000
	v_lshl_add_u64 v[90:91], v[90:91], 0, s[48:49]
	s_mov_b32 s46, 0
	v_add_u32_e32 v94, v212, v208
	s_waitcnt vmcnt(0)
; #define LAS __attribute__((address_space(3)))
; __device__ __forceinline__ float sigmoidf_(float x) { return __builtin_amdgcn_rcpf(1.0f + __expf(-x)); }
; __device__ __forceinline__ f32x4 mfma16(bf16x8 a, bf16x8 b, f32x4 c) { return __builtin_amdgcn_mfma_f32_16x16x32_bf16(a, b, c, 0, 0, 0); }
; template <int K>
; __device__ __forceinline__ void row_gemm(f32x4 (&acc)[4], LAS const unsigned char* Arow, const bf16_t* Bt, int fr, int fq) {
;     ...
; #pragma unroll
;     for (int n = 0; n < 4; ++n) acc[n] = (f32x4){0.f, 0.f, 0.f, 0.f};
; #pragma unroll
;     for (int ks = 0; ks < K / 32; ++ks) { const bf16x8 a = *(LAS const bf16x8*)(Arow + (ks * 32 + fq * 8) * 2);
; #pragma unroll
;         for (int n = 0; n < 4; ++n) acc[n] = mfma16(bw[ks][n], a, acc[n]); }
; __device__ __forceinline__ void rwkv_prep_tile(LAS unsigned char* lds, const PrepArgs& P, int tt, int tid) {
;     ...
;         row_gemm<64>(acc, LAw + i * SW, P.w2t + (size_t)cb * 64, fr, fq);
; #pragma unroll
;         for (int n = 0; n < 4; ++n) { const f32x4 a0v = *(LAS const f32x4*)(PRM + 1536 + cb + 16 * n + fq4), w0v = *(LAS const f32x4*)(PRM + 2048 + cb + 16 * n + fq4); f32x4 d;
; #pragma unroll
;             for (int j = 0; j < 4; ++j) { aa[n][j] = sigmoidf_(aa[n][j] + a0v[j]); d[j] = __expf(-0.6065306597f * sigmoidf_(acc[n][j] + w0v[j])); }
;             *(f32x4*)(P.Wd + ((size_t)p * SEQ + s0 + i) * 64 + 4 * fq4 + 4 * n) = d; }
.Lp4w_loop:
	ds_read_b128 v[50:53], v94
	ds_read_b128 v[54:57], v94 offset:64
	s_waitcnt lgkmcnt(0)
	v_mfma_f32_16x16x32_bf16 v[74:77], v[18:21], v[50:53], 0
	v_mfma_f32_16x16x32_bf16 v[78:81], v[26:29], v[50:53], 0
	v_mfma_f32_16x16x32_bf16 v[82:85], v[34:37], v[50:53], 0
	v_mfma_f32_16x16x32_bf16 v[86:89], v[42:45], v[50:53], 0
	v_mfma_f32_16x16x32_bf16 v[74:77], v[22:25], v[54:57], v[74:77]
	v_mfma_f32_16x16x32_bf16 v[78:81], v[30:33], v[54:57], v[78:81]
	v_mfma_f32_16x16x32_bf16 v[82:85], v[38:41], v[54:57], v[82:85]
	v_mfma_f32_16x16x32_bf16 v[86:89], v[46:49], v[54:57], v[86:89]
	s_nop 7
	s_nop 7
	s_nop 7
	v_add_f32_e32 v74, v74, v58
	v_add_f32_e32 v75, v75, v59
	v_add_f32_e32 v76, v76, v60
	v_add_f32_e32 v77, v77, v61
	v_add_f32_e32 v78, v78, v62
	v_add_f32_e32 v79, v79, v63
	v_add_f32_e32 v80, v80, v64
	v_add_f32_e32 v81, v81, v65
	v_add_f32_e32 v82, v82, v66
	v_add_f32_e32 v83, v83, v67
	v_add_f32_e32 v84, v84, v68
	v_add_f32_e32 v85, v85, v69
	v_add_f32_e32 v86, v86, v70
	v_add_f32_e32 v87, v87, v71
	v_add_f32_e32 v88, v88, v72
	v_add_f32_e32 v89, v89, v73
	v_mul_f32_e32 v74, 0xbfb8aa3b, v74
	v_mul_f32_e32 v75, 0xbfb8aa3b, v75
	v_mul_f32_e32 v76, 0xbfb8aa3b, v76
	v_mul_f32_e32 v77, 0xbfb8aa3b, v77
	v_mul_f32_e32 v78, 0xbfb8aa3b, v78
	v_mul_f32_e32 v79, 0xbfb8aa3b, v79
	v_mul_f32_e32 v80, 0xbfb8aa3b, v80
	v_mul_f32_e32 v81, 0xbfb8aa3b, v81
	v_mul_f32_e32 v82, 0xbfb8aa3b, v82
	v_mul_f32_e32 v83, 0xbfb8aa3b, v83
	v_mul_f32_e32 v84, 0xbfb8aa3b, v84
	v_mul_f32_e32 v85, 0xbfb8aa3b, v85
	v_mul_f32_e32 v86, 0xbfb8aa3b, v86
	v_mul_f32_e32 v87, 0xbfb8aa3b, v87
	v_mul_f32_e32 v88, 0xbfb8aa3b, v88
	v_mul_f32_e32 v89, 0xbfb8aa3b, v89
	v_exp_f32_e32 v74, v74
	v_exp_f32_e32 v75, v75
	v_exp_f32_e32 v76, v76
	v_exp_f32_e32 v77, v77
	v_exp_f32_e32 v78, v78
	v_exp_f32_e32 v79, v79
	v_exp_f32_e32 v80, v80
	v_exp_f32_e32 v81, v81
	v_exp_f32_e32 v82, v82
	v_exp_f32_e32 v83, v83
	v_exp_f32_e32 v84, v84
	v_exp_f32_e32 v85, v85
	v_exp_f32_e32 v86, v86
	v_exp_f32_e32 v87, v87
	v_exp_f32_e32 v88, v88
	v_exp_f32_e32 v89, v89
	v_add_f32_e32 v74, 1.0, v74
	v_add_f32_e32 v75, 1.0, v75
	v_add_f32_e32 v76, 1.0, v76
	v_add_f32_e32 v77, 1.0, v77
	v_add_f32_e32 v78, 1.0, v78
	v_add_f32_e32 v79, 1.0, v79
	v_add_f32_e32 v80, 1.0, v80
	v_add_f32_e32 v81, 1.0, v81
	v_add_f32_e32 v82, 1.0, v82
	v_add_f32_e32 v83, 1.0, v83
	v_add_f32_e32 v84, 1.0, v84
	v_add_f32_e32 v85, 1.0, v85
	v_add_f32_e32 v86, 1.0, v86
	v_add_f32_e32 v87, 1.0, v87
	v_add_f32_e32 v88, 1.0, v88
	v_add_f32_e32 v89, 1.0, v89
	v_rcp_f32_e32 v74, v74
	v_rcp_f32_e32 v75, v75
	v_rcp_f32_e32 v76, v76
	v_rcp_f32_e32 v77, v77
	v_rcp_f32_e32 v78, v78
	v_rcp_f32_e32 v79, v79
	v_rcp_f32_e32 v80, v80
	v_rcp_f32_e32 v81, v81
	v_rcp_f32_e32 v82, v82
	v_rcp_f32_e32 v83, v83
	v_rcp_f32_e32 v84, v84
	v_rcp_f32_e32 v85, v85
	v_rcp_f32_e32 v86, v86
	v_rcp_f32_e32 v87, v87
	v_rcp_f32_e32 v88, v88
	v_rcp_f32_e32 v89, v89
	v_mul_f32_e32 v74, 0xbf1b4598, v74
	v_mul_f32_e32 v75, 0xbf1b4598, v75
	v_mul_f32_e32 v76, 0xbf1b4598, v76
	v_mul_f32_e32 v77, 0xbf1b4598, v77
	v_mul_f32_e32 v78, 0xbf1b4598, v78
	v_mul_f32_e32 v79, 0xbf1b4598, v79
	v_mul_f32_e32 v80, 0xbf1b4598, v80
	v_mul_f32_e32 v81, 0xbf1b4598, v81
	v_mul_f32_e32 v82, 0xbf1b4598, v82
	v_mul_f32_e32 v83, 0xbf1b4598, v83
	v_mul_f32_e32 v84, 0xbf1b4598, v84
	v_mul_f32_e32 v85, 0xbf1b4598, v85
	v_mul_f32_e32 v86, 0xbf1b4598, v86
	v_mul_f32_e32 v87, 0xbf1b4598, v87
	v_mul_f32_e32 v88, 0xbf1b4598, v88
	v_mul_f32_e32 v89, 0xbf1b4598, v89
	v_mul_f32_e32 v74, 0x3fb8aa3b, v74
	v_mul_f32_e32 v75, 0x3fb8aa3b, v75
	v_mul_f32_e32 v76, 0x3fb8aa3b, v76
	v_mul_f32_e32 v77, 0x3fb8aa3b, v77
	v_mul_f32_e32 v78, 0x3fb8aa3b, v78
	v_mul_f32_e32 v79, 0x3fb8aa3b, v79
	v_mul_f32_e32 v80, 0x3fb8aa3b, v80
	v_mul_f32_e32 v81, 0x3fb8aa3b, v81
	v_mul_f32_e32 v82, 0x3fb8aa3b, v82
	v_mul_f32_e32 v83, 0x3fb8aa3b, v83
	v_mul_f32_e32 v84, 0x3fb8aa3b, v84
	v_mul_f32_e32 v85, 0x3fb8aa3b, v85
	v_mul_f32_e32 v86, 0x3fb8aa3b, v86
	v_mul_f32_e32 v87, 0x3fb8aa3b, v87
	v_mul_f32_e32 v88, 0x3fb8aa3b, v88
	v_mul_f32_e32 v89, 0x3fb8aa3b, v89
	v_exp_f32_e32 v74, v74
	v_exp_f32_e32 v75, v75
	v_exp_f32_e32 v76, v76
	v_exp_f32_e32 v77, v77
	v_exp_f32_e32 v78, v78
	v_exp_f32_e32 v79, v79
	v_exp_f32_e32 v80, v80
	v_exp_f32_e32 v81, v81
	v_exp_f32_e32 v82, v82
	v_exp_f32_e32 v83, v83
	v_exp_f32_e32 v84, v84
	v_exp_f32_e32 v85, v85
	v_exp_f32_e32 v86, v86
	v_exp_f32_e32 v87, v87
	v_exp_f32_e32 v88, v88
	v_exp_f32_e32 v89, v89
	s_nop 1
	global_store_dwordx4 v[90:91], v[74:77], off
	global_store_dwordx4 v[90:91], v[78:81], off offset:16
	global_store_dwordx4 v[90:91], v[82:85], off offset:32
	global_store_dwordx4 v[90:91], v[86:89], off offset:48
	s_nop 1
	v_lshl_add_u64 v[90:91], v[90:91], 0, s[60:61]
	v_add_u32_e32 v94, 0x900, v94
	s_add_i32 s46, s46, 16
	s_cmp_lg_u32 s46, 64
	s_cbranch_scc1 .Lp4w_loop
	s_branch .LBB0_417

; #define LAS __attribute__((address_space(3)))
; __device__ __forceinline__ void rwkv_prep_tile(LAS unsigned char* lds, const PrepArgs& P, int tt, int tid) {
;     ...
;         { const bf16_t* Up = hp ? Ut - 1792 : Ut; const unsigned pm = hp ? 0xffffffffu : 0u;
; #pragma unroll
;           for (int n = 0; n < 4; ++n) { const int c = cb + 16 * n + fq4;
;               uk[n] = *(const u32x2*)(Ut + 512 + c); ur[n] = *(const u32x2*)(Ut + c); uv[n] = *(const u32x2*)(Ut + 1024 + c);
;               pk[n] = *(const u32x2*)(Up + 512 + c); pr[n] = *(const u32x2*)(Up + c); pv[n] = *(const u32x2*)(Up + 1024 + c);
;               if (P.layer > 0) vf[n] = *(const f32x4*)(P.vfirst + (size_t)(t0 + i) * 512 + c); }
; #pragma unroll
;           for (int n = 0; n < 4; ++n) { pk[n].x &= pm; pk[n].y &= pm; pr[n].x &= pm; pr[n].y &= pm; pv[n].x &= pm; pv[n].y &= pm; } }
;         f32x4 aa[4], acc[4];
;         row_gemm<64>(aa, LAa + i * SW, P.a2t + (size_t)cb * 64, fr, fq);
;         row_gemm<64>(acc, LAw + i * SW, P.w2t + (size_t)cb * 64, fr, fq);
; #pragma unroll
;         for (int n = 0; n < 4; ++n) { const f32x4 a0v = *(LAS const f32x4*)(PRM + 1536 + cb + 16 * n + fq4), w0v = *(LAS const f32x4*)(PRM + 2048 + cb + 16 * n + fq4); f32x4 d;
.Lp4_skip_p:
	ds_read_b128 v[18:21], v215
	ds_read_b128 v[22:25], v215 offset:2048
	ds_read_b128 v[26:29], v215 offset:4096
	v_add_u32_e32 v62, v212, v208
	ds_read_b128 v[34:37], v62 offset:9216
	ds_read_b128 v[30:33], v62 offset:9280
	ds_read_b128 v[38:41], v215 offset:1024
	ds_read_b128 v[42:45], v215 offset:5120
	ds_read_b128 v[46:49], v215 offset:3072
	v_lshlrev_b32_e32 v162, 2, v98
	v_add_u32_e32 v71, s34, v162
	v_lshl_add_u64 v[88:89], v[156:157], 0, s[10:11]
	v_ashrrev_i32_e32 v163, 31, v162
	s_mov_b32 s24, 0xe100000
	v_ashrrev_i32_e32 v99, 31, v98
	s_waitcnt vmcnt(0) lgkmcnt(4)
	v_mfma_f32_16x16x32_bf16 v[18:21], v[18:21], v[34:37], 0
	s_waitcnt vmcnt(0) lgkmcnt(5)
	v_mfma_f32_16x16x32_bf16 v[54:57], v[26:29], v[34:37], 0
	v_mfma_f32_16x16x32_bf16 v[22:25], v[22:25], v[34:37], 0
	s_waitcnt vmcnt(0) lgkmcnt(1)
	v_mfma_f32_16x16x32_bf16 v[34:37], v[42:45], v[34:37], 0
	s_waitcnt vmcnt(0) lgkmcnt(0)
	v_mfma_f32_16x16x32_bf16 v[22:25], v[46:49], v[30:33], v[22:25]
	s_waitcnt vmcnt(0) lgkmcnt(0)
	s_waitcnt vmcnt(0) lgkmcnt(0)
	s_and_b64 vcc, exec, s[4:5]
	s_waitcnt vmcnt(0) lgkmcnt(0)
	s_waitcnt vmcnt(0) lgkmcnt(0)
	s_cmp_eq_u32 s35, 0
	s_cbranch_scc1 .Lp4_carry
	v_mov_b32_dpp v166, v128 row_ror:1 row_mask:0xf bank_mask:0x1
	v_mov_b32_dpp v167, v129 row_ror:1 row_mask:0xf bank_mask:0x1
	v_mov_b32_dpp v170, v130 row_ror:1 row_mask:0xf bank_mask:0x1
	v_mov_b32_dpp v171, v131 row_ror:1 row_mask:0xf bank_mask:0x1
	v_mov_b32_dpp v194, v132 row_ror:1 row_mask:0xf bank_mask:0x1
	v_mov_b32_dpp v195, v133 row_ror:1 row_mask:0xf bank_mask:0x1
	v_mov_b32_dpp v180, v134 row_ror:1 row_mask:0xf bank_mask:0x1
	v_mov_b32_dpp v181, v135 row_ror:1 row_mask:0xf bank_mask:0x1
	v_mov_b32_dpp v200, v136 row_ror:1 row_mask:0xf bank_mask:0x1
	v_mov_b32_dpp v201, v137 row_ror:1 row_mask:0xf bank_mask:0x1
	v_mov_b32_dpp v202, v138 row_ror:1 row_mask:0xf bank_mask:0x1
	v_mov_b32_dpp v203, v139 row_ror:1 row_mask:0xf bank_mask:0x1
	v_mov_b32_dpp v198, v140 row_ror:1 row_mask:0xf bank_mask:0x1
	v_mov_b32_dpp v199, v141 row_ror:1 row_mask:0xf bank_mask:0x1
	v_mov_b32_dpp v182, v142 row_ror:1 row_mask:0xf bank_mask:0x1
	v_mov_b32_dpp v183, v143 row_ror:1 row_mask:0xf bank_mask:0x1
	v_mov_b32_dpp v72, v144 row_ror:1 row_mask:0xf bank_mask:0x1
	v_mov_b32_dpp v73, v145 row_ror:1 row_mask:0xf bank_mask:0x1
	v_mov_b32_dpp v84, v146 row_ror:1 row_mask:0xf bank_mask:0x1
	v_mov_b32_dpp v85, v147 row_ror:1 row_mask:0xf bank_mask:0x1
	v_mov_b32_dpp v92, v148 row_ror:1 row_mask:0xf bank_mask:0x1
	v_mov_b32_dpp v93, v149 row_ror:1 row_mask:0xf bank_mask:0x1
	v_mov_b32_dpp v100, v150 row_ror:1 row_mask:0xf bank_mask:0x1
	v_mov_b32_dpp v101, v151 row_ror:1 row_mask:0xf bank_mask:0x1
	v_mov_b32_dpp v166, v164 row_shr:1 row_mask:0xf bank_mask:0xf
	v_mov_b32_dpp v167, v165 row_shr:1 row_mask:0xf bank_mask:0xf
	v_mov_b32_dpp v170, v168 row_shr:1 row_mask:0xf bank_mask:0xf
	v_mov_b32_dpp v171, v169 row_shr:1 row_mask:0xf bank_mask:0xf
	v_mov_b32_dpp v194, v176 row_shr:1 row_mask:0xf bank_mask:0xf
	v_mov_b32_dpp v195, v177 row_shr:1 row_mask:0xf bank_mask:0xf
	v_mov_b32_dpp v180, v172 row_shr:1 row_mask:0xf bank_mask:0xf
	v_mov_b32_dpp v181, v173 row_shr:1 row_mask:0xf bank_mask:0xf
	v_mov_b32_dpp v200, v196 row_shr:1 row_mask:0xf bank_mask:0xf
	v_mov_b32_dpp v201, v197 row_shr:1 row_mask:0xf bank_mask:0xf
	v_mov_b32_dpp v202, v184 row_shr:1 row_mask:0xf bank_mask:0xf
	v_mov_b32_dpp v203, v185 row_shr:1 row_mask:0xf bank_mask:0xf
	v_mov_b32_dpp v198, v178 row_shr:1 row_mask:0xf bank_mask:0xf
	v_mov_b32_dpp v199, v179 row_shr:1 row_mask:0xf bank_mask:0xf
	v_mov_b32_dpp v182, v174 row_shr:1 row_mask:0xf bank_mask:0xf
	v_mov_b32_dpp v183, v175 row_shr:1 row_mask:0xf bank_mask:0xf
	v_mov_b32_dpp v72, v74 row_shr:1 row_mask:0xf bank_mask:0xf
	v_mov_b32_dpp v73, v75 row_shr:1 row_mask:0xf bank_mask:0xf
	v_mov_b32_dpp v84, v86 row_shr:1 row_mask:0xf bank_mask:0xf
	v_mov_b32_dpp v85, v87 row_shr:1 row_mask:0xf bank_mask:0xf
	v_mov_b32_dpp v92, v104 row_shr:1 row_mask:0xf bank_mask:0xf
	v_mov_b32_dpp v93, v105 row_shr:1 row_mask:0xf bank_mask:0xf
	v_mov_b32_dpp v100, v102 row_shr:1 row_mask:0xf bank_mask:0xf
	v_mov_b32_dpp v101, v103 row_shr:1 row_mask:0xf bank_mask:0xf
.Lp4_carry:
	v_mov_b32_e32 v128, v164
	v_mov_b32_e32 v129, v165
	v_mov_b32_e32 v130, v168
	v_mov_b32_e32 v131, v169
	v_mov_b32_e32 v132, v176
	v_mov_b32_e32 v133, v177
	v_mov_b32_e32 v134, v172
	v_mov_b32_e32 v135, v173
	v_mov_b32_e32 v136, v196
	v_mov_b32_e32 v137, v197
	v_mov_b32_e32 v138, v184
	v_mov_b32_e32 v139, v185
	v_mov_b32_e32 v140, v178
	v_mov_b32_e32 v141, v179
	v_mov_b32_e32 v142, v174
	v_mov_b32_e32 v143, v175
	v_mov_b32_e32 v144, v74
	v_mov_b32_e32 v145, v75
	v_mov_b32_e32 v146, v86
	v_mov_b32_e32 v147, v87
	v_mov_b32_e32 v148, v104
	v_mov_b32_e32 v149, v105
	v_mov_b32_e32 v150, v102
	v_mov_b32_e32 v151, v103
	v_mfma_f32_16x16x32_bf16 v[26:29], v[38:41], v[30:33], v[18:21]
	s_nop 2
	ds_read_b128 v[18:21], v215 offset:6144
	ds_read_b128 v[38:41], v215 offset:7168
	s_waitcnt vmcnt(0) lgkmcnt(1)
	v_mfma_f32_16x16x32_bf16 v[18:21], v[18:21], v[30:33], v[54:57]
	s_nop 2
	s_waitcnt vmcnt(0) lgkmcnt(0)
	v_mfma_f32_16x16x32_bf16 v[30:33], v[38:41], v[30:33], v[34:37]
	s_nop 7
	s_nop 7
	s_nop 7
	s_nop 1
	v_add_u32_e32 v34, s31, v162
	ds_read_b128 v[46:49], v34
	ds_read_b128 v[42:45], v34 offset:64
	ds_read_b128 v[38:41], v34 offset:128
	ds_read_b128 v[34:37], v34 offset:192
	s_cbranch_vccnz .LBB0_427
	v_add_u32_e32 v58, v0, v208
	ds_read_b128 v[62:65], v58
	s_waitcnt lgkmcnt(0)
	v_mfma_f32_16x16x32_bf16 v[66:69], v[190:193], v[62:65], 0
	v_mfma_f32_16x16x32_bf16 v[58:61], v[216:219], v[62:65], 0
	v_mfma_f32_16x16x32_bf16 v[54:57], v[220:223], v[62:65], 0
	v_mfma_f32_16x16x32_bf16 v[62:65], v[224:227], v[62:65], 0
